# nt (streaming) stores for the bf16 weight copies written by the deferred conversion inside the retention loop (consumed phases later); plus nt on the final output stores
# baseline (speedup 1.0000x reference)
; __device__ __forceinline__ unsigned cvt_pk_bf16(float lo, float hi) { unsigned r; asm volatile("v_cvt_pk_bf16_f32 %0, %1, %2" : "=v"(r) : "v"(lo), "v"(hi)); return r; }
; __device__ __forceinline__ void cv_store(const CvU& u, int lane, const f32x4 (&v)[8], const f32x4 (&sc)[2]) {
;     ...
; #pragma unroll
;     for (int c = 0; c < 4; ++c) { bf16_t* dst = u.WT + (size_t)(u.rowperm ? u.n0d + 64 * (nq >> 3) + ((4 * nq + c) & 31) : u.n0d + 4 * nq + c) * u.K + u.k0 + 8 * kq;
;         u32x4 o;
;         o.x = cvt_pk_bf16(v[0][c] * sc[0][0], v[1][c] * sc[0][1]); o.y = cvt_pk_bf16(v[2][c] * sc[0][2], v[3][c] * sc[0][3]);
;         o.z = cvt_pk_bf16(v[4][c] * sc[1][0], v[5][c] * sc[1][1]); o.w = cvt_pk_bf16(v[6][c] * sc[1][2], v[7][c] * sc[1][3]);
;         *(u32x4*)dst = o; }
.LBB0_408:
	s_andn2_b64 vcc, exec, s[6:7]
	s_cbranch_vccnz .LBB0_356
	v_lshlrev_b32_e32 v0, 3, v100
	v_lshlrev_b32_e32 v100, 2, v100
	v_and_b32_e32 v101, 28, v100
	v_and_or_b32 v0, v0, 64, v101
	v_cndmask_b32_e64 v0, v0, v100, s[46:47]
	v_add_u32_e32 v0, s13, v0
	v_mad_i64_i32 v[100:101], s[6:7], s12, v0, 0
	s_ashr_i32 s71, s70, 31
	v_lshl_add_u64 v[100:101], v[100:101], 1, s[4:5]
	s_lshl_b64 s[6:7], s[70:71], 1
	v_lshl_add_u64 v[100:101], v[100:101], 0, s[6:7]
	v_lshlrev_b64 v[102:103], 1, v[98:99]
	s_waitcnt vmcnt(8)
	v_mul_f32_e32 v98, v186, v2
	v_mul_f32_e32 v99, v187, v6
	v_lshl_add_u64 v[104:105], v[100:101], 0, v[102:103]
	v_cvt_pk_bf16_f32 v98, v98, v99
	v_mul_f32_e32 v99, v188, v10
	v_mul_f32_e32 v100, v189, v14
	v_cvt_pk_bf16_f32 v99, v99, v100
	v_mul_f32_e32 v100, v182, v18
	v_mul_f32_e32 v101, v183, v22
	v_cvt_pk_bf16_f32 v100, v100, v101
	v_mul_f32_e32 v101, v184, v26
	v_mul_f32_e32 v106, v185, v30
	v_cvt_pk_bf16_f32 v101, v101, v106
	global_store_dwordx4 v[104:105], v[98:101], off nt
	v_mul_f32_e32 v106, v185, v31
	s_nop 0
	v_add_u32_e32 v98, 1, v0
	v_mad_i64_i32 v[98:99], s[14:15], s12, v98, 0
	v_lshl_add_u64 v[98:99], v[98:99], 1, s[4:5]
	v_lshl_add_u64 v[98:99], v[98:99], 0, s[6:7]
	v_lshl_add_u64 v[104:105], v[98:99], 0, v[102:103]
	v_mul_f32_e32 v98, v186, v3
	v_mul_f32_e32 v99, v187, v7
	v_cvt_pk_bf16_f32 v98, v98, v99
	v_mul_f32_e32 v99, v188, v11
	v_mul_f32_e32 v100, v189, v15
	v_cvt_pk_bf16_f32 v99, v99, v100
	v_mul_f32_e32 v100, v182, v19
	v_mul_f32_e32 v101, v183, v23
	v_cvt_pk_bf16_f32 v100, v100, v101
	v_mul_f32_e32 v101, v184, v27
	v_cvt_pk_bf16_f32 v101, v101, v106
	global_store_dwordx4 v[104:105], v[98:101], off nt
	v_mul_f32_e32 v106, v185, v32
	s_nop 0
	v_add_u32_e32 v98, 2, v0
	v_mad_i64_i32 v[98:99], s[14:15], s12, v98, 0
	v_lshl_add_u64 v[98:99], v[98:99], 1, s[4:5]
	v_lshl_add_u64 v[98:99], v[98:99], 0, s[6:7]
	v_lshl_add_u64 v[104:105], v[98:99], 0, v[102:103]
	v_mul_f32_e32 v98, v186, v4
	v_mul_f32_e32 v99, v187, v8
	v_cvt_pk_bf16_f32 v98, v98, v99
	v_mul_f32_e32 v99, v188, v12
	v_mul_f32_e32 v100, v189, v16
	v_cvt_pk_bf16_f32 v99, v99, v100
	v_mul_f32_e32 v100, v182, v20
	v_mul_f32_e32 v101, v183, v24
	v_cvt_pk_bf16_f32 v100, v100, v101
	v_mul_f32_e32 v101, v184, v28
	v_add_u32_e32 v0, 3, v0
	v_cvt_pk_bf16_f32 v101, v101, v106
	global_store_dwordx4 v[104:105], v[98:101], off nt
	s_nop 1
	v_mad_i64_i32 v[98:99], s[12:13], s12, v0, 0
	v_lshl_add_u64 v[98:99], v[98:99], 1, s[4:5]
	v_lshl_add_u64 v[98:99], v[98:99], 0, s[6:7]
	v_lshl_add_u64 v[102:103], v[98:99], 0, v[102:103]
	v_mul_f32_e32 v0, v186, v5
	v_mul_f32_e32 v98, v187, v9
	v_cvt_pk_bf16_f32 v98, v0, v98
	v_mul_f32_e32 v0, v188, v13
	v_mul_f32_e32 v99, v189, v17
	v_cvt_pk_bf16_f32 v99, v0, v99
	v_mul_f32_e32 v0, v182, v21
	v_mul_f32_e32 v100, v183, v25
	v_mul_f32_e32 v101, v185, v33
	v_cvt_pk_bf16_f32 v100, v0, v100
	v_mul_f32_e32 v0, v184, v29
	v_cvt_pk_bf16_f32 v101, v0, v101
	global_store_dwordx4 v[102:103], v[98:101], off nt
	s_branch .LBB0_356

; __device__ __forceinline__ unsigned cvt_pk_bf16(float lo, float hi) { unsigned r; asm volatile("v_cvt_pk_bf16_f32 %0, %1, %2" : "=v"(r) : "v"(lo), "v"(hi)); return r; }
; __device__ __forceinline__ void cv_store(const CvU& u, int lane, const f32x4 (&v)[8], const f32x4 (&sc)[2]) {
;     ...
; #pragma unroll
;     for (int c = 0; c < 4; ++c) { bf16_t* dst = u.WT + (size_t)(u.rowperm ? u.n0d + 64 * (nq >> 3) + ((4 * nq + c) & 31) : u.n0d + 4 * nq + c) * u.K + u.k0 + 8 * kq;
;         u32x4 o;
;         o.x = cvt_pk_bf16(v[0][c] * sc[0][0], v[1][c] * sc[0][1]); o.y = cvt_pk_bf16(v[2][c] * sc[0][2], v[3][c] * sc[0][3]);
;         o.z = cvt_pk_bf16(v[4][c] * sc[1][0], v[5][c] * sc[1][1]); o.w = cvt_pk_bf16(v[6][c] * sc[1][2], v[7][c] * sc[1][3]);
;         *(u32x4*)dst = o; }
.LBB0_458:
	s_andn2_b64 vcc, exec, s[6:7]
	s_cbranch_vccnz .LBB0_460
	v_lshlrev_b32_e32 v0, 3, v100
	v_lshlrev_b32_e32 v100, 2, v100
	v_and_b32_e32 v101, 28, v100
	v_and_or_b32 v0, v0, 64, v101
	v_cndmask_b32_e64 v0, v0, v100, s[46:47]
	v_add_u32_e32 v0, s11, v0
	v_mad_i64_i32 v[100:101], s[6:7], s12, v0, 0
	s_ashr_i32 s71, s70, 31
	v_lshl_add_u64 v[100:101], v[100:101], 1, s[4:5]
	s_lshl_b64 s[6:7], s[70:71], 1
	v_lshl_add_u64 v[100:101], v[100:101], 0, s[6:7]
	v_lshlrev_b64 v[102:103], 1, v[98:99]
	s_waitcnt vmcnt(0)
	v_mul_f32_e32 v98, v186, v2
	v_mul_f32_e32 v99, v187, v6
	v_lshl_add_u64 v[104:105], v[100:101], 0, v[102:103]
	v_cvt_pk_bf16_f32 v98, v98, v99
	v_mul_f32_e32 v99, v188, v10
	v_mul_f32_e32 v100, v189, v14
	v_cvt_pk_bf16_f32 v99, v99, v100
	v_mul_f32_e32 v100, v182, v18
	v_mul_f32_e32 v101, v183, v22
	v_cvt_pk_bf16_f32 v100, v100, v101
	v_mul_f32_e32 v101, v184, v26
	v_mul_f32_e32 v106, v185, v30
	v_cvt_pk_bf16_f32 v101, v101, v106
	global_store_dwordx4 v[104:105], v[98:101], off nt
	v_mul_f32_e32 v106, v185, v31
	s_nop 0
	v_add_u32_e32 v98, 1, v0
	v_mad_i64_i32 v[98:99], s[14:15], s12, v98, 0
	v_lshl_add_u64 v[98:99], v[98:99], 1, s[4:5]
	v_lshl_add_u64 v[98:99], v[98:99], 0, s[6:7]
	v_lshl_add_u64 v[104:105], v[98:99], 0, v[102:103]
	v_mul_f32_e32 v98, v186, v3
	v_mul_f32_e32 v99, v187, v7
	v_cvt_pk_bf16_f32 v98, v98, v99
	v_mul_f32_e32 v99, v188, v11
	v_mul_f32_e32 v100, v189, v15
	v_cvt_pk_bf16_f32 v99, v99, v100
	v_mul_f32_e32 v100, v182, v19
	v_mul_f32_e32 v101, v183, v23
	v_cvt_pk_bf16_f32 v100, v100, v101
	v_mul_f32_e32 v101, v184, v27
	v_cvt_pk_bf16_f32 v101, v101, v106
	global_store_dwordx4 v[104:105], v[98:101], off nt
	v_mul_f32_e32 v106, v185, v32
	s_nop 0
	v_add_u32_e32 v98, 2, v0
	v_mad_i64_i32 v[98:99], s[14:15], s12, v98, 0
	v_lshl_add_u64 v[98:99], v[98:99], 1, s[4:5]
	v_lshl_add_u64 v[98:99], v[98:99], 0, s[6:7]
	v_lshl_add_u64 v[104:105], v[98:99], 0, v[102:103]
	v_mul_f32_e32 v98, v186, v4
	v_mul_f32_e32 v99, v187, v8
	v_cvt_pk_bf16_f32 v98, v98, v99
	v_mul_f32_e32 v99, v188, v12
	v_mul_f32_e32 v100, v189, v16
	v_cvt_pk_bf16_f32 v99, v99, v100
	v_mul_f32_e32 v100, v182, v20
	v_mul_f32_e32 v101, v183, v24
	v_cvt_pk_bf16_f32 v100, v100, v101
	v_mul_f32_e32 v101, v184, v28
	v_add_u32_e32 v0, 3, v0
	v_cvt_pk_bf16_f32 v101, v101, v106
	global_store_dwordx4 v[104:105], v[98:101], off nt
	s_nop 1
	v_mad_i64_i32 v[98:99], s[12:13], s12, v0, 0
	v_lshl_add_u64 v[98:99], v[98:99], 1, s[4:5]
	v_lshl_add_u64 v[98:99], v[98:99], 0, s[6:7]
	v_lshl_add_u64 v[102:103], v[98:99], 0, v[102:103]
	v_mul_f32_e32 v0, v186, v5
	v_mul_f32_e32 v98, v187, v9
	v_cvt_pk_bf16_f32 v98, v0, v98
	v_mul_f32_e32 v0, v188, v13
	v_mul_f32_e32 v99, v189, v17
	v_cvt_pk_bf16_f32 v99, v0, v99
	v_mul_f32_e32 v0, v182, v21
	v_mul_f32_e32 v100, v183, v25
	v_mul_f32_e32 v101, v185, v33
	v_cvt_pk_bf16_f32 v100, v0, v100
	v_mul_f32_e32 v0, v184, v29
	v_cvt_pk_bf16_f32 v101, v0, v101
	global_store_dwordx4 v[102:103], v[98:101], off nt

; __device__ __forceinline__ unsigned cvt_pk_bf16(float lo, float hi) { unsigned r; asm volatile("v_cvt_pk_bf16_f32 %0, %1, %2" : "=v"(r) : "v"(lo), "v"(hi)); return r; }
; __device__ __forceinline__ void cv_store(const CvU& u, int lane, const f32x4 (&v)[8], const f32x4 (&sc)[2]) {
;     ...
; #pragma unroll
;     for (int c = 0; c < 4; ++c) { bf16_t* dst = u.WT + (size_t)(u.rowperm ? u.n0d + 64 * (nq >> 3) + ((4 * nq + c) & 31) : u.n0d + 4 * nq + c) * u.K + u.k0 + 8 * kq;
;         u32x4 o;
;         o.x = cvt_pk_bf16(v[0][c] * sc[0][0], v[1][c] * sc[0][1]); o.y = cvt_pk_bf16(v[2][c] * sc[0][2], v[3][c] * sc[0][3]);
;         o.z = cvt_pk_bf16(v[4][c] * sc[1][0], v[5][c] * sc[1][1]); o.w = cvt_pk_bf16(v[6][c] * sc[1][2], v[7][c] * sc[1][3]);
;         *(u32x4*)dst = o; }
; __device__ __forceinline__ void p2_ret(const Frame& F, ArgsP a, int layer) {
;     ...
;     while (cvhi < CV_HALF_ITEMS) { f32x4 cvv[8], cvsc[2]; const CvU cu = cv_decode(a, F.ws, cvhi, layer); cv_load(cu, lane, cvv, cvsc); cv_store(cu, lane, cvv, cvsc); cvhi += cvs; }
.LBB0_494:
	s_andn2_b64 vcc, exec, s[6:7]
	s_cbranch_vccnz .LBB0_468
	v_add_u32_e32 v47, s11, v47
	v_mad_i64_i32 v[48:49], s[6:7], s12, v47, 0
	s_ashr_i32 s5, s4, 31
	v_lshl_add_u64 v[48:49], v[48:49], 1, s[2:3]
	s_lshl_b64 s[4:5], s[4:5], 1
	v_lshl_add_u64 v[48:49], v[48:49], 0, s[4:5]
	v_lshlrev_b32_e32 v52, 1, v206
	v_mov_b32_e32 v53, v1
	s_waitcnt vmcnt(1)
	v_mul_f32_e32 v2, v2, v34
	v_lshl_add_u64 v[54:55], v[48:49], 0, v[52:53]
	v_mul_f32_e32 v6, v6, v35
	v_cvt_pk_bf16_f32 v48, v2, v6
	v_mul_f32_e32 v2, v10, v36
	v_mul_f32_e32 v6, v14, v37
	v_cvt_pk_bf16_f32 v49, v2, v6
	s_waitcnt vmcnt(0)
	v_mul_f32_e32 v2, v18, v38
	v_mul_f32_e32 v6, v22, v39
	v_cvt_pk_bf16_f32 v50, v2, v6
	v_mul_f32_e32 v2, v26, v40
	v_mul_f32_e32 v6, v30, v41
	v_cvt_pk_bf16_f32 v51, v2, v6
	v_add_u32_e32 v2, 1, v47
	global_store_dwordx4 v[54:55], v[48:51], off nt
	v_mul_f32_e32 v4, v4, v34
	v_mul_f32_e32 v6, v8, v35
	v_mad_i64_i32 v[48:49], s[6:7], s12, v2, 0
	v_lshl_add_u64 v[48:49], v[48:49], 1, s[2:3]
	v_lshl_add_u64 v[48:49], v[48:49], 0, s[4:5]
	v_mul_f32_e32 v2, v3, v34
	v_lshl_add_u64 v[54:55], v[48:49], 0, v[52:53]
	v_mul_f32_e32 v3, v7, v35
	v_cvt_pk_bf16_f32 v48, v2, v3
	v_mul_f32_e32 v2, v11, v36
	v_mul_f32_e32 v3, v15, v37
	v_cvt_pk_bf16_f32 v49, v2, v3
	v_mul_f32_e32 v2, v19, v38
	v_mul_f32_e32 v3, v23, v39
	v_cvt_pk_bf16_f32 v50, v2, v3
	v_mul_f32_e32 v2, v27, v40
	v_mul_f32_e32 v3, v31, v41
	v_cvt_pk_bf16_f32 v51, v2, v3
	v_add_u32_e32 v2, 2, v47
	v_mad_i64_i32 v[2:3], s[6:7], s12, v2, 0
	v_lshl_add_u64 v[2:3], v[2:3], 1, s[2:3]
	global_store_dwordx4 v[54:55], v[48:51], off nt
	v_lshl_add_u64 v[2:3], v[2:3], 0, s[4:5]
	v_lshl_add_u64 v[2:3], v[2:3], 0, v[52:53]
	v_cvt_pk_bf16_f32 v48, v4, v6
	v_mul_f32_e32 v4, v12, v36
	v_mul_f32_e32 v6, v16, v37
	v_cvt_pk_bf16_f32 v49, v4, v6
	v_mul_f32_e32 v4, v20, v38
	v_mul_f32_e32 v6, v24, v39
	v_cvt_pk_bf16_f32 v50, v4, v6
	v_mul_f32_e32 v4, v28, v40
	v_mul_f32_e32 v6, v32, v41
	v_cvt_pk_bf16_f32 v51, v4, v6
	global_store_dwordx4 v[2:3], v[48:51], off nt
	v_add_u32_e32 v2, 3, v47
	v_mad_i64_i32 v[2:3], s[6:7], s12, v2, 0
	v_lshl_add_u64 v[2:3], v[2:3], 1, s[2:3]
	v_lshl_add_u64 v[2:3], v[2:3], 0, s[4:5]
	v_lshl_add_u64 v[6:7], v[2:3], 0, v[52:53]
	v_mul_f32_e32 v2, v5, v34
	v_mul_f32_e32 v3, v9, v35
	v_cvt_pk_bf16_f32 v2, v2, v3
	v_mul_f32_e32 v3, v13, v36
	v_mul_f32_e32 v4, v17, v37
	v_cvt_pk_bf16_f32 v3, v3, v4
	v_mul_f32_e32 v4, v21, v38
	v_mul_f32_e32 v5, v25, v39
	v_cvt_pk_bf16_f32 v4, v4, v5
	v_mul_f32_e32 v5, v29, v40
	v_mul_f32_e32 v8, v33, v41
	v_cvt_pk_bf16_f32 v5, v5, v8
	global_store_dwordx4 v[6:7], v[2:5], off nt
	s_branch .LBB0_468
